# diff loop top: single scalar-selected wait+barrier instead of the three-way flag/branch chain
# speedup vs baseline: 1.0476x; 1.0031x over previous
.LBB0_539:
	s_waitcnt vmcnt(0) lgkmcnt(0)
	s_barrier
	s_branch .LBB0_545
.LBB0_540:
	s_waitcnt vmcnt(4) lgkmcnt(0)
	s_barrier

.LBB0_547:
	s_and_b32 s2, s9, 3
	s_mulk_i32 s2, 0x5000
	v_add_u32_e32 v75, s2, v74
	s_and_b32 s2, s43, 3
	s_mulk_i32 s2, 0x5000
	v_add_u32_e32 v172, s2, v74
	s_mov_b32 s10, s8
	s_mov_b32 s11, s8
	s_mov_b32 s9, s8
	s_waitcnt lgkmcnt(4)
	v_mfma_f32_32x32x16_bf16 v[156:171], v[2:5], v[70:73], v[156:171]
	v_exp_f32_e32 v100, v100
	v_exp_f32_e32 v101, v101
	v_exp_f32_e32 v102, v102
	s_waitcnt lgkmcnt(3)
	v_mfma_f32_32x32x16_bf16 v[140:155], v[6:9], v[70:73], v[140:155]
	ds_read_b128 v[66:69], v75 offset:6144
	v_exp_f32_e32 v103, v103
	v_exp_f32_e32 v104, v104
	v_exp_f32_e32 v105, v105
	v_mfma_f32_16x16x32_bf16 v[214:217], v[58:61], v[70:73], v[214:217]
	ds_read_b128 v[224:227], v75 offset:12288
	v_exp_f32_e32 v106, v106
	v_cvt_pk_bf16_f32 v182, v100, v101
	s_waitcnt lgkmcnt(4)
	v_mfma_f32_32x32x16_bf16 v[34:49], v[218:221], v[178:181], 0
	ds_read_b128 v[228:231], v75 offset:12800
	v_exp_f32_e32 v107, v107
	v_cvt_pk_bf16_f32 v183, v102, v103
	v_cvt_pk_bf16_f32 v184, v104, v105
	v_cvt_pk_bf16_f32 v185, v106, v107
	s_nop 1
	s_waitcnt lgkmcnt(4)
	v_mfma_f32_32x32x16_bf16 v[156:171], v[10:13], v[182:185], v[156:171]
	v_exp_f32_e32 v76, v76
	v_exp_f32_e32 v77, v77
	v_exp_f32_e32 v78, v78
	s_waitcnt lgkmcnt(3)
	v_mfma_f32_32x32x16_bf16 v[140:155], v[14:17], v[182:185], v[140:155]
	ds_read_b128 v[218:221], v75 offset:4608
	v_exp_f32_e32 v79, v79
	v_exp_f32_e32 v80, v80
	v_exp_f32_e32 v81, v81
	v_mfma_f32_16x16x32_bf16 v[214:217], v[58:61], v[182:185], v[214:217]
	ds_read_b128 v[232:235], v75 offset:14336
	v_exp_f32_e32 v82, v82
	v_cvt_pk_bf16_f32 v70, v76, v77
	s_waitcnt lgkmcnt(4)
	v_mfma_f32_32x32x16_bf16 v[34:49], v[66:69], v[174:177], v[34:49]
	ds_read_b128 v[236:239], v75 offset:14848
	v_exp_f32_e32 v83, v83
	v_cvt_pk_bf16_f32 v71, v78, v79
	v_cvt_pk_bf16_f32 v72, v80, v81
	v_cvt_pk_bf16_f32 v73, v82, v83
	s_nop 1
	s_waitcnt lgkmcnt(4)
	v_mfma_f32_32x32x16_bf16 v[156:171], v[224:227], v[70:73], v[156:171]
	v_exp_f32_e32 v84, v84
	v_exp_f32_e32 v85, v85
	v_exp_f32_e32 v86, v86
	s_waitcnt lgkmcnt(3)
	v_mfma_f32_32x32x16_bf16 v[140:155], v[228:231], v[70:73], v[140:155]
	ds_read_b128 v[66:69], v75 offset:6656
	v_exp_f32_e32 v87, v87
	v_exp_f32_e32 v88, v88
	v_exp_f32_e32 v89, v89
	v_mfma_f32_16x16x32_bf16 v[214:217], v[58:61], v[70:73], v[214:217]
	v_exp_f32_e32 v90, v90
	v_cvt_pk_bf16_f32 v182, v84, v85
	s_waitcnt lgkmcnt(3)
	v_mfma_f32_32x32x16_bf16 v[18:33], v[218:221], v[178:181], 0
	v_exp_f32_e32 v91, v91
	v_cvt_pk_bf16_f32 v183, v86, v87
	v_cvt_pk_bf16_f32 v184, v88, v89
	v_cvt_pk_bf16_f32 v185, v90, v91
	s_nop 1
	s_waitcnt lgkmcnt(2)
	v_mfma_f32_32x32x16_bf16 v[156:171], v[232:235], v[182:185], v[156:171]
	v_exp_f32_e32 v34, v34
	v_exp_f32_e32 v35, v35
	v_exp_f32_e32 v36, v36
	s_waitcnt lgkmcnt(1)
	v_mfma_f32_32x32x16_bf16 v[140:155], v[236:239], v[182:185], v[140:155]
	ds_read_b128 v[218:221], v172
	v_exp_f32_e32 v37, v37
	v_exp_f32_e32 v38, v38
	v_exp_f32_e32 v39, v39
	v_mfma_f32_16x16x32_bf16 v[214:217], v[58:61], v[182:185], v[214:217]
	v_exp_f32_e32 v40, v40
	v_cvt_pk_bf16_f32 v70, v34, v35
	s_waitcnt lgkmcnt(1)
	v_mfma_f32_32x32x16_bf16 v[18:33], v[66:69], v[174:177], v[18:33]
	v_exp_f32_e32 v41, v41
	v_cvt_pk_bf16_f32 v71, v36, v37
	v_cvt_pk_bf16_f32 v72, v38, v39
	v_cvt_pk_bf16_f32 v73, v40, v41
	s_nop 1
	s_cmp_lg_u32 s43, s26
	s_cbranch_scc0 .Ldiff_b_last
	v_mfma_f32_32x32x16_bf16 v[124:139], v[2:5], v[70:73], v[124:139]
	v_exp_f32_e32 v42, v42
	v_exp_f32_e32 v43, v43
	v_exp_f32_e32 v44, v44
	v_mfma_f32_32x32x16_bf16 v[108:123], v[6:9], v[70:73], v[108:123]
	ds_read_b128 v[66:69], v172 offset:2048
	v_exp_f32_e32 v45, v45
	v_exp_f32_e32 v46, v46
	v_exp_f32_e32 v47, v47
	v_mfma_f32_16x16x32_bf16 v[214:217], v[62:65], v[70:73], v[214:217]
	v_exp_f32_e32 v48, v48
	v_cvt_pk_bf16_f32 v182, v42, v43
	s_waitcnt lgkmcnt(1)
	v_mfma_f32_32x32x16_bf16 v[92:107], v[218:221], v[50:53], 0
	v_exp_f32_e32 v49, v49
	v_cvt_pk_bf16_f32 v183, v44, v45
	v_cvt_pk_bf16_f32 v184, v46, v47
	v_cvt_pk_bf16_f32 v185, v48, v49
	s_nop 1
	v_mfma_f32_32x32x16_bf16 v[124:139], v[10:13], v[182:185], v[124:139]
	v_exp_f32_e32 v18, v18
	v_exp_f32_e32 v19, v19
	v_exp_f32_e32 v20, v20
	v_mfma_f32_32x32x16_bf16 v[108:123], v[14:17], v[182:185], v[108:123]
	ds_read_b128 v[218:221], v172 offset:512
	v_exp_f32_e32 v21, v21
	v_exp_f32_e32 v22, v22
	v_exp_f32_e32 v23, v23
	v_mfma_f32_16x16x32_bf16 v[214:217], v[62:65], v[182:185], v[214:217]
	v_exp_f32_e32 v24, v24
	v_cvt_pk_bf16_f32 v70, v18, v19
	s_waitcnt lgkmcnt(1)
	v_mfma_f32_32x32x16_bf16 v[92:107], v[66:69], v[54:57], v[92:107]
	v_exp_f32_e32 v25, v25
	v_cvt_pk_bf16_f32 v71, v20, v21
	v_cvt_pk_bf16_f32 v72, v22, v23
	v_cvt_pk_bf16_f32 v73, v24, v25
	s_nop 1
	v_mfma_f32_32x32x16_bf16 v[124:139], v[224:227], v[70:73], v[124:139]
	v_exp_f32_e32 v26, v26
	v_exp_f32_e32 v27, v27
	v_exp_f32_e32 v28, v28
	v_mfma_f32_32x32x16_bf16 v[108:123], v[228:231], v[70:73], v[108:123]
	ds_read_b128 v[66:69], v172 offset:2560
	v_exp_f32_e32 v29, v29
	v_exp_f32_e32 v30, v30
	v_exp_f32_e32 v31, v31
	v_mfma_f32_16x16x32_bf16 v[214:217], v[62:65], v[70:73], v[214:217]
	ds_read_b128 v[2:5], v172 offset:8192
	v_exp_f32_e32 v32, v32
	v_cvt_pk_bf16_f32 v182, v26, v27
	s_waitcnt lgkmcnt(2)
	v_mfma_f32_32x32x16_bf16 v[76:91], v[218:221], v[50:53], 0
	ds_read_b128 v[6:9], v172 offset:8704
	v_exp_f32_e32 v33, v33
	v_cvt_pk_bf16_f32 v183, v28, v29
	v_cvt_pk_bf16_f32 v184, v30, v31
	v_cvt_pk_bf16_f32 v185, v32, v33
	s_nop 1
	v_mfma_f32_32x32x16_bf16 v[124:139], v[232:235], v[182:185], v[124:139]
	v_exp_f32_e32 v92, v92
	v_exp_f32_e32 v93, v93
	v_exp_f32_e32 v94, v94
	v_mfma_f32_32x32x16_bf16 v[108:123], v[236:239], v[182:185], v[108:123]
	ds_read_b128 v[218:221], v172 offset:4096
	v_exp_f32_e32 v95, v95
	v_exp_f32_e32 v96, v96
	v_exp_f32_e32 v97, v97
	v_mfma_f32_16x16x32_bf16 v[214:217], v[62:65], v[182:185], v[214:217]
	ds_read_b128 v[10:13], v172 offset:10240
	v_exp_f32_e32 v98, v98
	v_cvt_pk_bf16_f32 v70, v92, v93
	s_waitcnt lgkmcnt(4)
	v_mfma_f32_32x32x16_bf16 v[76:91], v[66:69], v[54:57], v[76:91]
	ds_read_b128 v[14:17], v172 offset:10752
	v_exp_f32_e32 v99, v99
	v_cvt_pk_bf16_f32 v71, v94, v95
	v_cvt_pk_bf16_f32 v72, v96, v97
	v_cvt_pk_bf16_f32 v73, v98, v99
	s_nop 1
	s_add_i32 s2, s43, 1
	s_add_u32 s44, s44, 0x1000
	s_addc_u32 s45, s45, 0
	s_add_u32 s46, s46, 0x2000
	s_addc_u32 s47, s47, 0
	s_mov_b32 s43, s2
	s_add_i32 s9, s43, -1
	s_cmp_ge_u32 s9, s28
	s_cbranch_scc0 .LBB0_540
	s_branch .LBB0_539
